# final RMSNorm reads the sums of squares with sc1 (the residual rows were already nt): L1 invalidate dropped at the last barrier too
# speedup vs baseline: 1.0864x; 1.0001x over previous
.LBB0_571:
	s_add_u32 s24, s28, s20
	v_lshl_add_u64 v[20:21], s[28:29], 0, v[18:19]
	s_addc_u32 s25, s29, s21
	v_add_co_u32_e32 v40, vcc, s33, v20
	s_add_u32 s26, s24, 0x100000
	s_nop 0
	v_addc_co_u32_e32 v41, vcc, 0, v21, vcc
	s_addc_u32 s27, s25, 0
	global_load_dwordx4 v[20:23], v211, s[24:25] sc1
	global_load_dwordx4 v[24:27], v211, s[24:25] offset:64 sc1
	global_load_dwordx4 v[28:31], v[40:41], off nt
	global_load_dwordx4 v[32:35], v[40:41], off offset:1024 nt
	global_load_dwordx4 v[36:39], v[40:41], off offset:2048 nt
	s_nop 0
	global_load_dwordx4 v[40:43], v[40:41], off offset:3072 nt
	s_nop 0
	global_load_dwordx4 v[44:47], v163, s[26:27] offset:32 sc1
	global_load_dwordx4 v[48:51], v163, s[26:27] offset:16 sc1
	global_load_dwordx4 v[52:55], v163, s[26:27] offset:48 sc1
	s_add_u32 s24, s24, 0x100040
	s_addc_u32 s25, s25, 0
	global_load_dwordx4 v[56:59], v163, s[24:25] offset:32 sc1
	global_load_dwordx4 v[60:63], v163, s[24:25] offset:16 sc1
	global_load_dwordx4 v[64:67], v163, s[24:25] offset:48 sc1
	s_add_i32 s12, s12, s14
	s_add_u32 s20, s20, s22
	s_addc_u32 s21, s21, s23
	v_lshl_add_u64 v[18:19], v[18:19], 0, s[18:19]
	s_cmpk_gt_i32 s12, 0x3fff
	s_waitcnt vmcnt(11)
	v_mov_b32_e32 v68, v20
	v_mov_b32_e32 v20, v22
	s_waitcnt vmcnt(10)
	v_mov_b32_e32 v22, v24
	v_mov_b32_e32 v24, v26
	s_waitcnt vmcnt(5)
	v_mov_b32_e32 v69, v44
	v_mov_b32_e32 v44, v21
	v_mov_b32_e32 v21, v46
	v_mov_b32_e32 v46, v23
	s_waitcnt vmcnt(4)
	v_mov_b32_e32 v86, v48
	s_waitcnt vmcnt(3)
	v_mov_b32_e32 v87, v52
	v_mov_b32_e32 v52, v49
	v_mov_b32_e32 v48, v50
	v_mov_b32_e32 v49, v54
	v_mov_b32_e32 v54, v51
	v_pk_add_f32 v[44:45], v[68:69], v[44:45]
	v_pk_add_f32 v[20:21], v[20:21], v[46:47]
	v_pk_add_f32 v[46:47], v[86:87], v[52:53]
	v_pk_add_f32 v[48:49], v[48:49], v[54:55]
	s_waitcnt vmcnt(2)
	v_mov_b32_e32 v23, v56
	v_mov_b32_e32 v56, v25
	v_mov_b32_e32 v25, v58
	v_mov_b32_e32 v58, v27
	s_waitcnt vmcnt(1)
	v_mov_b32_e32 v26, v60
	s_waitcnt vmcnt(0)
	v_mov_b32_e32 v27, v64
	v_mov_b32_e32 v64, v61
	v_mov_b32_e32 v50, v62
	v_mov_b32_e32 v51, v66
	v_mov_b32_e32 v66, v63
	v_pk_add_f32 v[20:21], v[44:45], v[20:21]
	v_pk_add_f32 v[44:45], v[46:47], v[48:49]
	v_pk_add_f32 v[22:23], v[22:23], v[56:57]
	v_pk_add_f32 v[24:25], v[24:25], v[58:59]
	v_pk_add_f32 v[26:27], v[26:27], v[64:65]
	v_pk_add_f32 v[46:47], v[50:51], v[66:67]
	v_pk_add_f32 v[20:21], v[20:21], v[44:45]
	v_lshlrev_b32_e32 v70, 16, v28
	v_add_f32_e32 v44, v20, v21
	v_pk_add_f32 v[20:21], v[22:23], v[24:25]
	v_pk_add_f32 v[22:23], v[26:27], v[46:47]
	v_fmamk_f32 v24, v44, 0x3a800000, v209
	v_pk_add_f32 v[20:21], v[20:21], v[22:23]
	v_rsq_f32_e32 v22, v24
	v_add_f32_e32 v20, v20, v21
	v_fmamk_f32 v20, v20, 0x3a800000, v209
	v_rsq_f32_e32 v44, v20
	v_and_b32_e32 v71, 0xffff0000, v28
	v_lshlrev_b32_e32 v28, 16, v29
	v_and_b32_e32 v29, 0xffff0000, v29
	v_lshlrev_b32_e32 v72, 16, v30
	v_and_b32_e32 v73, 0xffff0000, v30
	v_lshlrev_b32_e32 v30, 16, v31
	v_and_b32_e32 v31, 0xffff0000, v31
	v_lshlrev_b32_e32 v74, 16, v32
	v_and_b32_e32 v75, 0xffff0000, v32
	v_lshlrev_b32_e32 v32, 16, v33
	v_and_b32_e32 v33, 0xffff0000, v33
	v_lshlrev_b32_e32 v76, 16, v34
	v_and_b32_e32 v77, 0xffff0000, v34
	v_lshlrev_b32_e32 v34, 16, v35
	v_and_b32_e32 v35, 0xffff0000, v35
	v_pk_mul_f32 v[20:21], v[22:23], v[70:71] op_sel_hi:[0,1]
	v_pk_mul_f32 v[24:25], v[22:23], v[28:29] op_sel_hi:[0,1]
	v_lshlrev_b32_e32 v78, 16, v36
	v_and_b32_e32 v79, 0xffff0000, v36
	v_lshlrev_b32_e32 v36, 16, v37
	v_and_b32_e32 v37, 0xffff0000, v37
	v_pk_mul_f32 v[28:29], v[22:23], v[72:73] op_sel_hi:[0,1]
	v_pk_mul_f32 v[26:27], v[22:23], v[30:31] op_sel_hi:[0,1]
	v_pk_mul_f32 v[46:47], v[22:23], v[74:75] op_sel_hi:[0,1]
	v_pk_mul_f32 v[30:31], v[22:23], v[32:33] op_sel_hi:[0,1]
	v_pk_mul_f32 v[32:33], v[22:23], v[76:77] op_sel_hi:[0,1]
	v_pk_mul_f32 v[34:35], v[22:23], v[34:35] op_sel_hi:[0,1]
	v_pk_mul_f32 v[22:23], v[6:7], v[24:25]
	v_pk_mul_f32 v[20:21], v[4:5], v[20:21]
	v_lshlrev_b32_e32 v80, 16, v38
	v_and_b32_e32 v81, 0xffff0000, v38
	v_lshlrev_b32_e32 v38, 16, v39
	v_and_b32_e32 v39, 0xffff0000, v39
	v_lshlrev_b32_e32 v82, 16, v40
	v_and_b32_e32 v83, 0xffff0000, v40
	v_lshlrev_b32_e32 v40, 16, v41
	v_and_b32_e32 v41, 0xffff0000, v41
	v_lshlrev_b32_e32 v84, 16, v42
	v_and_b32_e32 v85, 0xffff0000, v42
	v_lshlrev_b32_e32 v42, 16, v43
	v_and_b32_e32 v43, 0xffff0000, v43
	v_pk_mul_f32 v[26:27], v[2:3], v[26:27]
	v_pk_mul_f32 v[24:25], v[0:1], v[28:29]
	v_pk_mul_f32 v[30:31], v[14:15], v[30:31]
	v_pk_mul_f32 v[28:29], v[12:13], v[46:47]
	v_pk_mul_f32 v[34:35], v[10:11], v[34:35]
	v_pk_mul_f32 v[32:33], v[8:9], v[32:33]
	global_store_dwordx4 v[16:17], v[20:23], off offset:-4096
	global_store_dwordx4 v[16:17], v[24:27], off offset:-4080
	global_store_dwordx4 v[16:17], v[28:31], off offset:-2048
	global_store_dwordx4 v[16:17], v[32:35], off offset:-2032
	v_pk_mul_f32 v[20:21], v[44:45], v[78:79] op_sel_hi:[0,1]
	v_pk_mul_f32 v[22:23], v[44:45], v[36:37] op_sel_hi:[0,1]
	v_pk_mul_f32 v[24:25], v[44:45], v[80:81] op_sel_hi:[0,1]
	v_pk_mul_f32 v[26:27], v[44:45], v[38:39] op_sel_hi:[0,1]
	v_pk_mul_f32 v[28:29], v[44:45], v[82:83] op_sel_hi:[0,1]
	v_pk_mul_f32 v[30:31], v[44:45], v[40:41] op_sel_hi:[0,1]
	v_pk_mul_f32 v[32:33], v[44:45], v[84:85] op_sel_hi:[0,1]
	v_pk_mul_f32 v[34:35], v[44:45], v[42:43] op_sel_hi:[0,1]
	v_pk_mul_f32 v[22:23], v[6:7], v[22:23]
	v_pk_mul_f32 v[20:21], v[4:5], v[20:21]
	v_pk_mul_f32 v[26:27], v[2:3], v[26:27]
	v_pk_mul_f32 v[24:25], v[0:1], v[24:25]
	v_pk_mul_f32 v[30:31], v[14:15], v[30:31]
	v_pk_mul_f32 v[28:29], v[12:13], v[28:29]
	v_pk_mul_f32 v[34:35], v[10:11], v[34:35]
	v_pk_mul_f32 v[32:33], v[8:9], v[32:33]
	global_store_dwordx4 v[16:17], v[20:23], off
	global_store_dwordx4 v[16:17], v[24:27], off offset:16
	global_store_dwordx4 v[16:17], v[28:31], off offset:2048
	global_store_dwordx4 v[16:17], v[32:35], off offset:2064
	v_lshl_add_u64 v[16:17], v[16:17], 0, s[16:17]
	s_cbranch_scc0 .LBB0_571
	v_readlane_b32 s22, v255, 4
	s_mov_b32 s50, s3
	v_readlane_b32 s23, v255, 5
	s_branch .LBB0_574

.Lmy_xb_poll:
	s_mov_b64 exec, s[14:15]
	s_mov_b32 s3, 0
	s_sub_i32 s18, s68, 1
	s_lshl_b32 s18, 1, s18
	s_and_b32 s18, s18, 0x460c
	s_cmp_lg_u32 s18, 0
	s_cbranch_scc1 .Lmy_xb_noinv2
	buffer_inv sc1
